# grid-barrier poll loops: back-off lengthened from s_sleep 1 to s_sleep 2, on top of ring peel
# speedup vs baseline: 1.0050x; 1.0050x over previous
; __global__ void __launch_bounds__(NTHREADS) mega_fwd(P p) {
;     ...
;     if (p.ws == nullptr) grid.sync();
.LBB0_36:
	s_sleep 2
	global_load_dword v2, v0, s[2:3] offset:32 sc1
	s_waitcnt vmcnt(0)
	v_and_b32_e32 v2, 0xffff0000, v2
	v_cmp_ne_u32_e32 vcc, v2, v1
	s_or_b64 s[10:11], vcc, s[10:11]
	s_andn2_b64 exec, exec, s[10:11]
	s_cbranch_execnz .LBB0_36

; __device__ __forceinline__ unsigned xb_ld(unsigned* p)              { return __hip_atomic_load(p, __ATOMIC_RELAXED, __HIP_MEMORY_SCOPE_AGENT); }
; __device__ __forceinline__ void xcd_barrier_complete(unsigned* bar, unsigned x, unsigned& nloc, unsigned& nx) {
;     const unsigned G = gridDim.x * gridDim.y * gridDim.z;
;     unsigned sum, cnt, mine, sp = 0u;
;     for (;;) {
;         sum = 0u; cnt = 0u; mine = 0u;
; #pragma unroll
;         for (unsigned j = 0; j < 16; ++j) { const unsigned c = xb_ld(&bar[XB_XCNT(j)]); sum += c; cnt += (c > 0u) ? 1u : 0u; mine = (j == x) ? c : mine; }
;         if (sum == G) break;
;         __builtin_amdgcn_s_sleep(1);
;         if ((++sp & 255u) == 0u) { if (xb_ld(&bar[XB_TMO])) break; if (sp > XB_SPIN_CAP) { atomicAdd(&bar[XB_TMO], 1u); break; } }
;     }
;     nloc = mine > 0u ? mine : 1u; nx = cnt > 0u ? cnt : 1u;
; }
.LBB0_45:
	global_load_dword v15, v16, s[36:37] offset:1024 sc1
	s_waitcnt lgkmcnt(0)
	global_load_dword v0, v16, s[36:37] offset:1280 sc1
	global_load_dword v1, v16, s[36:37] offset:1536 sc1
	global_load_dword v2, v16, s[36:37] offset:1792 sc1
	global_load_dword v3, v16, s[36:37] offset:2048 sc1
	global_load_dword v4, v16, s[36:37] offset:2304 sc1
	global_load_dword v5, v16, s[36:37] offset:2560 sc1
	global_load_dword v6, v16, s[36:37] offset:2816 sc1
	global_load_dword v7, v16, s[36:37] offset:3072 sc1
	global_load_dword v8, v16, s[36:37] offset:3328 sc1
	global_load_dword v9, v16, s[36:37] offset:3584 sc1
	global_load_dword v10, v16, s[36:37] offset:3840 sc1
	global_load_dword v11, v16, s[6:7] sc1
	global_load_dword v12, v16, s[8:9] sc1
	global_load_dword v13, v16, s[10:11] sc1
	global_load_dword v14, v16, s[12:13] sc1
	s_mov_b64 s[14:15], -1
	s_mov_b64 s[16:17], -1
	s_waitcnt vmcnt(14)
	v_add_u32_e32 v17, v0, v15
	s_waitcnt vmcnt(13)
	v_add_u32_e32 v17, v17, v1
	s_waitcnt vmcnt(12)
	v_add_u32_e32 v17, v17, v2
	s_waitcnt vmcnt(11)
	v_add_u32_e32 v17, v17, v3
	s_waitcnt vmcnt(10)
	v_add_u32_e32 v17, v17, v4
	s_waitcnt vmcnt(9)
	v_add_u32_e32 v17, v17, v5
	s_waitcnt vmcnt(8)
	v_add_u32_e32 v17, v17, v6
	s_waitcnt vmcnt(7)
	v_add_u32_e32 v17, v17, v7
	s_waitcnt vmcnt(6)
	v_add_u32_e32 v17, v17, v8
	s_waitcnt vmcnt(5)
	v_add_u32_e32 v17, v17, v9
	s_waitcnt vmcnt(4)
	v_add_u32_e32 v17, v17, v10
	s_waitcnt vmcnt(3)
	v_add_u32_e32 v17, v17, v11
	s_waitcnt vmcnt(2)
	v_add_u32_e32 v17, v17, v12
	s_waitcnt vmcnt(1)
	v_add_u32_e32 v17, v17, v13
	s_waitcnt vmcnt(0)
	v_add_u32_e32 v17, v17, v14
	v_cmp_eq_u32_e32 vcc, s5, v17
	s_cbranch_vccnz .LBB0_44
	s_and_b32 s14, s20, 0xff
	s_cmp_eq_u32 s14, 0
	s_mov_b64 s[14:15], -1
	s_mov_b64 s[18:19], -1
	s_sleep 2
	s_cbranch_scc1 .LBB0_49
	s_and_b64 vcc, exec, s[18:19]
	s_cbranch_vccz .LBB0_44

; __device__ __forceinline__ unsigned xb_ld(unsigned* p)              { return __hip_atomic_load(p, __ATOMIC_RELAXED, __HIP_MEMORY_SCOPE_AGENT); }
; __device__ __forceinline__ unsigned xb_add(unsigned* p, unsigned v) { return __hip_atomic_fetch_add(p, v, __ATOMIC_RELAXED, __HIP_MEMORY_SCOPE_AGENT); }
; #define XB_SPIN(cond, bar) do { unsigned _sp = 0; while (cond) { __builtin_amdgcn_s_sleep(1); \
;     if ((++_sp & 255u) == 0u) { if (xb_ld(&(bar)[XB_TMO])) break; if (_sp > XB_SPIN_CAP) { atomicAdd(&(bar)[XB_TMO], 1u); break; } } } } while (0)
; __device__ __forceinline__ void xcd_barrier(const XcdBarrier& b) {
;     ...
;             else XB_SPIN(xb_ld(&bar[XB_TOPGEN]) == tg, bar);
;             __builtin_amdgcn_fence(__ATOMIC_ACQUIRE, "agent");
;             xb_add(&bar[XB_XGEN(b.x)], 1u);
;             asm volatile("s_waitcnt vmcnt(0)" ::: "memory");
;         } else {
;             XB_SPIN(xb_ld(&bar[XB_XGEN(b.x)]) == gen, bar);
.LBB0_63:
	s_and_b32 s22, s5, 0xff
	s_mov_b64 s[20:21], -1
	s_cmp_lg_u32 s22, 0
	s_mov_b64 s[24:25], -1
	s_sleep 2
	s_cbranch_scc0 .LBB0_66
	s_and_b64 vcc, exec, s[24:25]
	s_cbranch_vccz .LBB0_62

; __device__ __forceinline__ unsigned xb_ld(unsigned* p)              { return __hip_atomic_load(p, __ATOMIC_RELAXED, __HIP_MEMORY_SCOPE_AGENT); }
; __device__ __forceinline__ unsigned xb_add(unsigned* p, unsigned v) { return __hip_atomic_fetch_add(p, v, __ATOMIC_RELAXED, __HIP_MEMORY_SCOPE_AGENT); }
; #define XB_SPIN(cond, bar) do { unsigned _sp = 0; while (cond) { __builtin_amdgcn_s_sleep(1); \
;     if ((++_sp & 255u) == 0u) { if (xb_ld(&(bar)[XB_TMO])) break; if (_sp > XB_SPIN_CAP) { atomicAdd(&(bar)[XB_TMO], 1u); break; } } } } while (0)
; __device__ __forceinline__ void xcd_barrier(const XcdBarrier& b) {
;     ...
;             else XB_SPIN(xb_ld(&bar[XB_TOPGEN]) == tg, bar);
;             __builtin_amdgcn_fence(__ATOMIC_ACQUIRE, "agent");
;             xb_add(&bar[XB_XGEN(b.x)], 1u);
;             asm volatile("s_waitcnt vmcnt(0)" ::: "memory");
;         } else {
;             XB_SPIN(xb_ld(&bar[XB_XGEN(b.x)]) == gen, bar);
.LBB0_80:
	s_and_b32 s24, s5, 0xff
	s_cmp_lg_u32 s24, 0
	s_mov_b64 s[26:27], -1
	s_sleep 2
	s_cbranch_scc0 .LBB0_83
	s_mov_b64 s[28:29], -1
	s_and_b64 vcc, exec, s[26:27]
	s_cbranch_vccz .LBB0_79

; __device__ __forceinline__ unsigned xb_ld(unsigned* p)              { return __hip_atomic_load(p, __ATOMIC_RELAXED, __HIP_MEMORY_SCOPE_AGENT); }
; __device__ __forceinline__ void xcd_barrier_complete(unsigned* bar, unsigned x, unsigned& nloc, unsigned& nx) {
;     const unsigned G = gridDim.x * gridDim.y * gridDim.z;
;     unsigned sum, cnt, mine, sp = 0u;
;     for (;;) {
;         sum = 0u; cnt = 0u; mine = 0u;
; #pragma unroll
;         for (unsigned j = 0; j < 16; ++j) { const unsigned c = xb_ld(&bar[XB_XCNT(j)]); sum += c; cnt += (c > 0u) ? 1u : 0u; mine = (j == x) ? c : mine; }
;         if (sum == G) break;
;         __builtin_amdgcn_s_sleep(1);
;         if ((++sp & 255u) == 0u) { if (xb_ld(&bar[XB_TMO])) break; if (sp > XB_SPIN_CAP) { atomicAdd(&bar[XB_TMO], 1u); break; } }
;     }
;     nloc = mine > 0u ? mine : 1u; nx = cnt > 0u ? cnt : 1u;
; }
.LBB0_108:
	v_readlane_b32 s6, v253, 11
	v_readlane_b32 s7, v253, 12
	global_load_dword v12, v1, s[36:37] offset:1024 sc1
	global_load_dword v0, v1, s[36:37] offset:1280 sc1
	s_waitcnt lgkmcnt(0)
	global_load_dword v2, v1, s[36:37] offset:1536 sc1
	global_load_dword v3, v1, s[36:37] offset:1792 sc1
	global_load_dword v4, v1, s[36:37] offset:2048 sc1
	global_load_dword v5, v1, s[36:37] offset:2304 sc1
	global_load_dword v6, v1, s[36:37] offset:2560 sc1
	global_load_dword v7, v1, s[36:37] offset:2816 sc1
	global_load_dword v8, v1, s[36:37] offset:3072 sc1
	global_load_dword v9, v1, s[36:37] offset:3328 sc1
	global_load_dword v10, v1, s[36:37] offset:3584 sc1
	global_load_dword v11, v1, s[36:37] offset:3840 sc1
	global_load_dword v13, v1, s[6:7] sc1
	v_readlane_b32 s6, v253, 13
	v_readlane_b32 s7, v253, 14
	v_readlane_b32 s8, v253, 8
	s_waitcnt vmcnt(11)
	v_add_u32_e32 v17, v0, v12
	s_nop 1
	global_load_dword v14, v1, s[6:7] sc1
	v_readlane_b32 s6, v253, 15
	v_readlane_b32 s7, v253, 16
	s_waitcnt vmcnt(11)
	v_add_u32_e32 v17, v17, v2
	s_waitcnt vmcnt(10)
	v_add_u32_e32 v17, v17, v3
	s_waitcnt vmcnt(9)
	v_add_u32_e32 v17, v17, v4
	s_waitcnt vmcnt(8)
	v_add_u32_e32 v17, v17, v5
	s_waitcnt vmcnt(7)
	v_add_u32_e32 v17, v17, v6
	global_load_dword v15, v1, s[6:7] sc1
	v_readlane_b32 s6, v253, 17
	v_readlane_b32 s7, v253, 18
	s_waitcnt vmcnt(7)
	v_add_u32_e32 v17, v17, v7
	s_waitcnt vmcnt(6)
	v_add_u32_e32 v17, v17, v8
	s_waitcnt vmcnt(5)
	v_add_u32_e32 v17, v17, v9
	s_waitcnt vmcnt(4)
	v_add_u32_e32 v17, v17, v10
	s_waitcnt vmcnt(3)
	v_add_u32_e32 v17, v17, v11
	global_load_dword v16, v1, s[6:7] sc1
	s_waitcnt vmcnt(3)
	v_add_u32_e32 v17, v17, v13
	s_mov_b64 s[6:7], -1
	s_waitcnt vmcnt(2)
	v_add_u32_e32 v17, v17, v14
	s_waitcnt vmcnt(1)
	v_add_u32_e32 v17, v17, v15
	s_waitcnt vmcnt(0)
	v_add_u32_e32 v17, v17, v16
	v_cmp_eq_u32_e32 vcc, s8, v17
	s_mov_b64 s[8:9], -1
	s_cbranch_vccnz .LBB0_107
	s_and_b32 s6, s12, 0xff
	s_cmp_eq_u32 s6, 0
	s_mov_b64 s[6:7], -1
	s_mov_b64 s[10:11], -1
	s_sleep 2
	s_cbranch_scc1 .LBB0_112
	s_and_b64 vcc, exec, s[10:11]
	s_cbranch_vccz .LBB0_107

; __device__ __forceinline__ unsigned xb_ld(unsigned* p)              { return __hip_atomic_load(p, __ATOMIC_RELAXED, __HIP_MEMORY_SCOPE_AGENT); }
; __device__ __forceinline__ unsigned xb_add(unsigned* p, unsigned v) { return __hip_atomic_fetch_add(p, v, __ATOMIC_RELAXED, __HIP_MEMORY_SCOPE_AGENT); }
; #define XB_SPIN(cond, bar) do { unsigned _sp = 0; while (cond) { __builtin_amdgcn_s_sleep(1); \
;     if ((++_sp & 255u) == 0u) { if (xb_ld(&(bar)[XB_TMO])) break; if (_sp > XB_SPIN_CAP) { atomicAdd(&(bar)[XB_TMO], 1u); break; } } } } while (0)
; __device__ __forceinline__ void xcd_barrier(const XcdBarrier& b) {
;     ...
;             else XB_SPIN(xb_ld(&bar[XB_TOPGEN]) == tg, bar);
;             __builtin_amdgcn_fence(__ATOMIC_ACQUIRE, "agent");
;             xb_add(&bar[XB_XGEN(b.x)], 1u);
;             asm volatile("s_waitcnt vmcnt(0)" ::: "memory");
;         } else {
;             XB_SPIN(xb_ld(&bar[XB_XGEN(b.x)]) == gen, bar);
.LBB0_124:
	s_and_b32 s16, s20, 0xff
	s_mov_b64 s[14:15], -1
	s_cmp_lg_u32 s16, 0
	s_mov_b64 s[18:19], -1
	s_sleep 2
	s_cbranch_scc0 .LBB0_127
	s_and_b64 vcc, exec, s[18:19]
	s_cbranch_vccz .LBB0_123

; __device__ __forceinline__ unsigned xb_ld(unsigned* p)              { return __hip_atomic_load(p, __ATOMIC_RELAXED, __HIP_MEMORY_SCOPE_AGENT); }
; __device__ __forceinline__ unsigned xb_add(unsigned* p, unsigned v) { return __hip_atomic_fetch_add(p, v, __ATOMIC_RELAXED, __HIP_MEMORY_SCOPE_AGENT); }
; #define XB_SPIN(cond, bar) do { unsigned _sp = 0; while (cond) { __builtin_amdgcn_s_sleep(1); \
;     if ((++_sp & 255u) == 0u) { if (xb_ld(&(bar)[XB_TMO])) break; if (_sp > XB_SPIN_CAP) { atomicAdd(&(bar)[XB_TMO], 1u); break; } } } } while (0)
; __device__ __forceinline__ void xcd_barrier(const XcdBarrier& b) {
;     ...
;             else XB_SPIN(xb_ld(&bar[XB_TOPGEN]) == tg, bar);
;             __builtin_amdgcn_fence(__ATOMIC_ACQUIRE, "agent");
;             xb_add(&bar[XB_XGEN(b.x)], 1u);
;             asm volatile("s_waitcnt vmcnt(0)" ::: "memory");
;         } else {
;             XB_SPIN(xb_ld(&bar[XB_XGEN(b.x)]) == gen, bar);
.LBB0_141:
	s_and_b32 s18, s22, 0xff
	s_mov_b64 s[16:17], -1
	s_cmp_lg_u32 s18, 0
	s_mov_b64 s[20:21], -1
	s_sleep 2
	s_cbranch_scc0 .LBB0_144
	s_and_b64 vcc, exec, s[20:21]
	s_cbranch_vccz .LBB0_140

; __device__ __forceinline__ unsigned xb_ld(unsigned* p)              { return __hip_atomic_load(p, __ATOMIC_RELAXED, __HIP_MEMORY_SCOPE_AGENT); }
; __device__ __forceinline__ void xcd_barrier_complete(unsigned* bar, unsigned x, unsigned& nloc, unsigned& nx) {
;     const unsigned G = gridDim.x * gridDim.y * gridDim.z;
;     unsigned sum, cnt, mine, sp = 0u;
;     for (;;) {
;         sum = 0u; cnt = 0u; mine = 0u;
; #pragma unroll
;         for (unsigned j = 0; j < 16; ++j) { const unsigned c = xb_ld(&bar[XB_XCNT(j)]); sum += c; cnt += (c > 0u) ? 1u : 0u; mine = (j == x) ? c : mine; }
;         if (sum == G) break;
;         __builtin_amdgcn_s_sleep(1);
;         if ((++sp & 255u) == 0u) { if (xb_ld(&bar[XB_TMO])) break; if (sp > XB_SPIN_CAP) { atomicAdd(&bar[XB_TMO], 1u); break; } }
;     }
;     nloc = mine > 0u ? mine : 1u; nx = cnt > 0u ? cnt : 1u;
; }
.LBB0_792:
	v_readlane_b32 s12, v253, 11
	v_readlane_b32 s13, v253, 12
	global_load_dword v12, v1, s[36:37] offset:1024 sc1
	global_load_dword v0, v1, s[36:37] offset:1280 sc1
	s_waitcnt lgkmcnt(0)
	global_load_dword v2, v1, s[36:37] offset:1536 sc1
	global_load_dword v3, v1, s[36:37] offset:1792 sc1
	global_load_dword v4, v1, s[36:37] offset:2048 sc1
	global_load_dword v5, v1, s[36:37] offset:2304 sc1
	global_load_dword v6, v1, s[36:37] offset:2560 sc1
	global_load_dword v7, v1, s[36:37] offset:2816 sc1
	global_load_dword v8, v1, s[36:37] offset:3072 sc1
	global_load_dword v9, v1, s[36:37] offset:3328 sc1
	global_load_dword v10, v1, s[36:37] offset:3584 sc1
	global_load_dword v11, v1, s[36:37] offset:3840 sc1
	global_load_dword v13, v1, s[12:13] sc1
	v_readlane_b32 s12, v253, 13
	v_readlane_b32 s13, v253, 14
	v_readlane_b32 s14, v253, 8
	s_waitcnt vmcnt(11)
	v_add_u32_e32 v17, v0, v12
	s_nop 1
	global_load_dword v14, v1, s[12:13] sc1
	v_readlane_b32 s12, v253, 15
	v_readlane_b32 s13, v253, 16
	s_waitcnt vmcnt(11)
	v_add_u32_e32 v17, v17, v2
	s_waitcnt vmcnt(10)
	v_add_u32_e32 v17, v17, v3
	s_waitcnt vmcnt(9)
	v_add_u32_e32 v17, v17, v4
	s_waitcnt vmcnt(8)
	v_add_u32_e32 v17, v17, v5
	s_waitcnt vmcnt(7)
	v_add_u32_e32 v17, v17, v6
	global_load_dword v15, v1, s[12:13] sc1
	v_readlane_b32 s12, v253, 17
	v_readlane_b32 s13, v253, 18
	s_waitcnt vmcnt(7)
	v_add_u32_e32 v17, v17, v7
	s_waitcnt vmcnt(6)
	v_add_u32_e32 v17, v17, v8
	s_waitcnt vmcnt(5)
	v_add_u32_e32 v17, v17, v9
	s_waitcnt vmcnt(4)
	v_add_u32_e32 v17, v17, v10
	s_waitcnt vmcnt(3)
	v_add_u32_e32 v17, v17, v11
	global_load_dword v16, v1, s[12:13] sc1
	s_waitcnt vmcnt(3)
	v_add_u32_e32 v17, v17, v13
	s_mov_b64 s[12:13], -1
	s_waitcnt vmcnt(2)
	v_add_u32_e32 v17, v17, v14
	s_waitcnt vmcnt(1)
	v_add_u32_e32 v17, v17, v15
	s_waitcnt vmcnt(0)
	v_add_u32_e32 v17, v17, v16
	v_cmp_eq_u32_e32 vcc, s14, v17
	s_mov_b64 s[14:15], -1
	s_cbranch_vccnz .LBB0_791
	s_and_b32 s12, s18, 0xff
	s_cmp_eq_u32 s12, 0
	s_mov_b64 s[12:13], -1
	s_mov_b64 s[16:17], -1
	s_sleep 2
	s_cbranch_scc1 .LBB0_796
	s_and_b64 vcc, exec, s[16:17]
	s_cbranch_vccz .LBB0_791

; __device__ __forceinline__ unsigned xb_ld(unsigned* p)              { return __hip_atomic_load(p, __ATOMIC_RELAXED, __HIP_MEMORY_SCOPE_AGENT); }
; __device__ __forceinline__ unsigned xb_add(unsigned* p, unsigned v) { return __hip_atomic_fetch_add(p, v, __ATOMIC_RELAXED, __HIP_MEMORY_SCOPE_AGENT); }
; #define XB_SPIN(cond, bar) do { unsigned _sp = 0; while (cond) { __builtin_amdgcn_s_sleep(1); \
;     if ((++_sp & 255u) == 0u) { if (xb_ld(&(bar)[XB_TMO])) break; if (_sp > XB_SPIN_CAP) { atomicAdd(&(bar)[XB_TMO], 1u); break; } } } } while (0)
; __device__ __forceinline__ void xcd_barrier(const XcdBarrier& b) {
;     ...
;             else XB_SPIN(xb_ld(&bar[XB_TOPGEN]) == tg, bar);
;             __builtin_amdgcn_fence(__ATOMIC_ACQUIRE, "agent");
;             xb_add(&bar[XB_XGEN(b.x)], 1u);
;             asm volatile("s_waitcnt vmcnt(0)" ::: "memory");
;         } else {
;             XB_SPIN(xb_ld(&bar[XB_XGEN(b.x)]) == gen, bar);
.LBB0_808:
	s_and_b32 s22, s26, 0xff
	s_mov_b64 s[20:21], -1
	s_cmp_lg_u32 s22, 0
	s_mov_b64 s[24:25], -1
	s_sleep 2
	s_cbranch_scc0 .LBB0_811
	s_and_b64 vcc, exec, s[24:25]
	s_cbranch_vccz .LBB0_807
